# speedup vs baseline: 1.0154x; 1.0022x over previous
; __global__ void __launch_bounds__(512, 2) fwd_megakernel(Params kp_) {
;     ...
;                             bf16x8 fa1[4], fb1[2], fk1[2]; float uv1[4]; float eg1;
;                             bf16x8 fa2[4], fb2[2], fk2[2]; float uv2[4]; float eg2;
;                             GS_LOAD(fa, fb, fk, uv, eg, 0); GS_LOAD(fa1, fb1, fk1, uv1, eg1, 1);
.LBB0_850:
	v_lshl_add_u64 v[168:169], s[86:87], 0, v[156:157]
	s_mov_b32 s6, 0x8000
	v_add_co_u32_e32 v72, vcc, s6, v168
	v_lshl_add_u64 v[166:167], s[86:87], 0, v[154:155]
	s_nop 0
	v_addc_co_u32_e32 v73, vcc, 0, v169, vcc
	s_mov_b32 s6, 0x4804000
	global_load_dwordx4 v[92:95], v[72:73], off
	global_load_dwordx4 v[96:99], v[72:73], off offset:64
	global_load_dwordx4 v[100:103], v[72:73], off offset:128
	global_load_dwordx4 v[104:107], v[72:73], off offset:192
	v_add_co_u32_e32 v72, vcc, s6, v166
	v_lshl_add_u64 v[162:163], s[86:87], 0, v[152:153]
	s_nop 0
	v_addc_co_u32_e32 v73, vcc, 0, v167, vcc
	s_mov_b32 s6, 0x2808000
	v_add_co_u32_e32 v74, vcc, s6, v162
	v_lshl_add_u64 v[164:165], s[86:87], 0, v[150:151]
	s_nop 0
	v_addc_co_u32_e32 v75, vcc, 0, v163, vcc
	s_mov_b32 s6, 0x18808000
	v_add_co_u32_e32 v108, vcc, s6, v164
	s_add_u32 s10, s86, s8
	s_nop 0
	v_addc_co_u32_e32 v109, vcc, 0, v165, vcc
	s_mov_b64 exec, s[0:1]
	global_load_dwordx4 v[88:91], v[72:73], off
	s_mov_b64 exec, -1
	v_mov_b32_e32 v84, 0
	v_mov_b32_e32 v85, 0
	v_mov_b32_e32 v86, 0
	v_mov_b32_e32 v87, 0
	v_cmp_le_u32_e32 vcc, 0x180, v199
	s_mov_b64 exec, vcc
	global_load_dwordx4 v[84:87], v[72:73], off offset:1024
	s_mov_b64 exec, -1
	global_load_dwordx4 v[76:79], v[74:75], off
	s_nop 0
	global_load_dwordx4 v[72:75], v[74:75], off offset:1024
	s_addc_u32 s11, s87, s9
	s_mov_b64 exec, s[100:101]
	global_load_ushort v145, v[108:109], off
	global_load_ushort v182, v[108:109], off offset:16
	global_load_ushort v183, v[108:109], off offset:32
	global_load_ushort v184, v[108:109], off offset:48
	s_mov_b64 exec, -1
	global_load_dword v160, v239, s[10:11] offset:8
	ds_read_b128 v[108:111], v129
	ds_read_b128 v[112:115], v129 offset:64
	ds_read_b128 v[116:119], v129 offset:128
	ds_read_b128 v[120:123], v129 offset:192
	v_cndmask_b32_e64 v124, 0, 1, s[0:1]
	v_cmp_ne_u32_e64 s[6:7], 1, v124
	s_andn2_b64 vcc, exec, s[0:1]
	s_mov_b64 s[12:13], -1
	s_cbranch_vccnz .LBB0_852
	s_waitcnt lgkmcnt(3)
	v_mfma_f32_16x16x32_bf16 v[124:127], v[108:111], v[60:63], 0
	s_mov_b64 s[12:13], 0
	s_waitcnt lgkmcnt(2)
	v_mfma_f32_16x16x32_bf16 v[124:127], v[112:115], v[48:51], v[124:127]
	s_waitcnt lgkmcnt(1)
	v_mfma_f32_16x16x32_bf16 v[124:127], v[116:119], v[52:55], v[124:127]
	s_waitcnt lgkmcnt(0)
	v_mfma_f32_16x16x32_bf16 v[124:127], v[120:123], v[56:59], v[124:127]

.LBB0_856:
	s_waitcnt vmcnt(13)
	v_pk_mul_f32 v[42:43], v[82:83], v[146:147] op_sel_hi:[1,0]
	v_pk_mul_f32 v[40:41], v[80:81], v[146:147] op_sel_hi:[1,0]
	s_mov_b32 s12, 0xc000
	v_add_co_u32_e32 v60, vcc, s12, v168
	s_waitcnt lgkmcnt(1)
	v_mfma_f32_16x16x32_bf16 v[8:11], v[48:51], v[8:11], v[40:43]
	v_addc_co_u32_e32 v61, vcc, 0, v169, vcc
	s_mov_b32 s12, 0x4806000
	s_waitcnt lgkmcnt(0)
	v_mfma_f32_16x16x32_bf16 v[68:71], v[52:55], v[12:15], v[8:11]
	v_add_co_u32_e32 v12, vcc, s12, v166
	s_mov_b32 s12, 0x280c000
	s_nop 0
	v_addc_co_u32_e32 v13, vcc, 0, v167, vcc
	v_add_co_u32_e32 v14, vcc, s12, v162
	s_nop 2
	v_cvt_pk_bf16_f32 v8, v68, s0
	v_addc_co_u32_e32 v15, vcc, 0, v163, vcc
	s_mov_b32 s12, 0x1880c000
	v_cvt_pk_bf16_f32 v9, v69, s0
	v_cvt_pk_bf16_f32 v10, v70, s0
	v_cvt_pk_bf16_f32 v11, v71, s0
	ds_write_b16 v180, v8
	ds_write_b16 v180, v9 offset:272
	ds_write_b16 v180, v10 offset:544
	ds_write_b16 v180, v11 offset:816
	v_add_co_u32_e32 v62, vcc, s12, v164
	s_waitcnt lgkmcnt(0)
	s_barrier
	global_load_dwordx4 v[48:51], v[60:61], off offset:64
	global_load_dwordx4 v[52:55], v[60:61], off offset:128
	v_addc_co_u32_e32 v63, vcc, 0, v165, vcc
	global_load_dwordx4 v[56:59], v[60:61], off offset:192
	s_mov_b64 exec, s[0:1]
	global_load_dwordx4 v[40:43], v[12:13], off
	s_mov_b64 exec, -1
	global_load_dwordx4 v[8:11], v[14:15], off
	v_mov_b32_e32 v44, 0
	v_mov_b32_e32 v45, 0
	v_mov_b32_e32 v46, 0
	v_mov_b32_e32 v47, 0
	v_cmp_le_u32_e32 vcc, 0x180, v199
	s_mov_b64 exec, vcc
	global_load_dwordx4 v[44:47], v[12:13], off offset:1024
	s_mov_b64 exec, -1
	s_nop 0
	global_load_dwordx4 v[12:15], v[14:15], off offset:1024
	s_nop 0
	s_mov_b64 exec, s[100:101]
	global_load_ushort v125, v[62:63], off
	global_load_ushort v159, v[62:63], off offset:16
	global_load_ushort v126, v[62:63], off offset:32
	global_load_ushort v127, v[62:63], off offset:48
	s_mov_b64 exec, -1
	s_nop 0
	global_load_dwordx4 v[60:63], v[60:61], off
	s_nop 0
	global_load_dword v124, v239, s[10:11] offset:12
	ds_read_b128 v[80:83], v181
	ds_read_b128 v[108:111], v181 offset:64
	ds_read_b128 v[112:115], v181 offset:128
	ds_read_b128 v[116:119], v181 offset:192
	s_and_b64 vcc, exec, s[6:7]
	s_mov_b64 s[12:13], -1
	s_cbranch_vccnz .LBB0_858
	s_waitcnt lgkmcnt(3)
	v_mfma_f32_16x16x32_bf16 v[120:123], v[80:83], v[24:27], 0
	s_mov_b64 s[12:13], 0
	s_waitcnt lgkmcnt(2)
	v_mfma_f32_16x16x32_bf16 v[120:123], v[108:111], v[28:31], v[120:123]
	s_waitcnt lgkmcnt(1)
	v_mfma_f32_16x16x32_bf16 v[120:123], v[112:115], v[32:35], v[120:123]
	s_waitcnt lgkmcnt(0)
	v_mfma_f32_16x16x32_bf16 v[120:123], v[116:119], v[36:39], v[120:123]

.LBB0_862:
	v_pk_mul_f32 v[16:17], v[146:147], v[68:69] op_sel:[1,0]
	v_pk_mul_f32 v[18:19], v[146:147], v[70:71] op_sel:[1,0]
	s_mov_b32 s12, 0x10000
	s_waitcnt lgkmcnt(1)
	v_mfma_f32_16x16x32_bf16 v[0:3], v[24:27], v[0:3], v[16:19]
	s_waitcnt lgkmcnt(0)
	v_mfma_f32_16x16x32_bf16 v[80:83], v[28:31], v[4:7], v[0:3]
	s_nop 7
	v_cvt_pk_bf16_f32 v0, v80, s0
	v_cvt_pk_bf16_f32 v1, v81, s0
	v_cvt_pk_bf16_f32 v2, v82, s0
	v_cvt_pk_bf16_f32 v3, v83, s0
	ds_write_b16 v180, v0
	ds_write_b16 v180, v1 offset:272
	ds_write_b16 v180, v2 offset:544
	ds_write_b16 v180, v3 offset:816
	v_add_co_u32_e32 v0, vcc, s12, v168
	s_waitcnt lgkmcnt(0)
	s_barrier
	s_mov_b32 s12, 0x4808000
	s_nop 0
	v_addc_co_u32_e32 v1, vcc, 0, v169, vcc
	global_load_dwordx4 v[24:27], v[0:1], off
	global_load_dwordx4 v[28:31], v[0:1], off offset:64
	global_load_dwordx4 v[32:35], v[0:1], off offset:128
	global_load_dwordx4 v[36:39], v[0:1], off offset:192
	v_add_co_u32_e32 v0, vcc, s12, v166
	s_mov_b32 s12, 0x2810000
	s_nop 0
	v_addc_co_u32_e32 v1, vcc, 0, v167, vcc
	v_add_co_u32_e32 v4, vcc, s12, v162
	s_nop 1
	v_addc_co_u32_e32 v5, vcc, 0, v163, vcc
	s_mov_b64 exec, s[0:1]
	global_load_dwordx4 v[20:23], v[0:1], off
	s_mov_b64 exec, -1
	v_mov_b32_e32 v16, 0
	v_mov_b32_e32 v17, 0
	v_mov_b32_e32 v18, 0
	v_mov_b32_e32 v19, 0
	v_cmp_le_u32_e32 vcc, 0x180, v199
	s_mov_b64 exec, vcc
	global_load_dwordx4 v[16:19], v[0:1], off offset:1024
	s_mov_b64 exec, -1
	s_nop 0
	global_load_dwordx4 v[0:3], v[4:5], off
	s_nop 0
	global_load_dwordx4 v[4:7], v[4:5], off offset:1024
	v_add_co_u32_e32 v64, vcc, 0x18810000, v164
	s_nop 1
	v_addc_co_u32_e32 v65, vcc, 0, v165, vcc
	s_mov_b64 exec, s[100:101]
	global_load_ushort v122, v[64:65], off
	global_load_ushort v123, v[64:65], off offset:16
	global_load_ushort v120, v[64:65], off offset:32
	global_load_ushort v121, v[64:65], off offset:48
	s_mov_b64 exec, -1
	global_load_dword v147, v239, s[10:11] offset:16
	ds_read_b128 v[64:67], v181
	ds_read_b128 v[68:71], v181 offset:64
	ds_read_b128 v[108:111], v181 offset:128
	ds_read_b128 v[112:115], v181 offset:192
	s_and_b64 vcc, exec, s[6:7]
	s_mov_b64 s[10:11], -1
	s_cbranch_vccnz .LBB0_864
	s_waitcnt vmcnt(38) lgkmcnt(3)
	v_mfma_f32_16x16x32_bf16 v[116:119], v[64:67], v[92:95], 0
	s_mov_b64 s[10:11], 0
	s_waitcnt vmcnt(37) lgkmcnt(2)
	v_mfma_f32_16x16x32_bf16 v[116:119], v[68:71], v[96:99], v[116:119]
	s_waitcnt vmcnt(36) lgkmcnt(1)
	v_mfma_f32_16x16x32_bf16 v[116:119], v[108:111], v[100:103], v[116:119]
	s_waitcnt vmcnt(35) lgkmcnt(0)
	v_mfma_f32_16x16x32_bf16 v[116:119], v[112:115], v[104:107], v[116:119]
